# group start stagger ordered by row block (XCC-major) instead of interleaved across XCCs, s_sleep 10
# baseline (speedup 1.0000x reference)
; #define LAS __attribute__((address_space(3)))
; __device__ __forceinline__ bool attn_unit(const Ptrs& P, LAS unsigned char* lds, int unit, int tid, int wave, int lane, bool pre, int nxt) {
;     const int n = unit & 31, kh = (unit >> 5) & 3, b = unit >> 7;
;     const int g = wave & 3, q0 = 64 * (wave >> 2), h = kh * 4 + g, r = lane & 31, hh = lane >> 5;
;     unsigned char* ws = P.ws;
;     bf16_t* Qb = (bf16_t*)(ws + WS_Q) + (size_t)(b * SEQ + n * 128 + q0) * DM + h * 64;
;     const bf16_t* Kg = (const bf16_t*)(ws + WS_K) + (size_t)b * SEQ * KVW + kh * 64; const bf16_t* Vg = (const bf16_t*)(ws + WS_VT) + (size_t)(b * 4 + kh) * 64 * SEQ;
;     const bf16_t* Kcg = (const bf16_t*)(ws + WS_KC) + (size_t)b * CTX * KVW + kh * 64; const bf16_t* Vcg = (const bf16_t*)(ws + WS_VCT) + (size_t)(b * 4 + kh) * 64 * CTX;
;     float mq = fabsf(P.qg[lane]), mk = fabsf(P.kg[lane]);
; #pragma unroll
;     for (int o = 1; o < 64; o <<= 1) { mq = fmaxf(mq, __shfl_xor(mq, o)); mk = fmaxf(mk, __shfl_xor(mk, o)); }
;     const float sink2 = P.sink[h] * LOG2E; const float mshift = fmaxf(64.0f * QSCALE * mq * mk, sink2);
;     bf16x8_t qf[2][4];
; #pragma unroll
;     for (int cb = 0; cb < 2; ++cb)
; #pragma unroll
;         for (int ds = 0; ds < 4; ++ds) qf[cb][ds] = __builtin_nontemporal_load((const bf16x8_t*)(Qb + (size_t)(32 * cb + r) * DM + 16 * ds + 8 * hh));
;     f32x16 o[2][2];
; #pragma unroll
;     for (int db = 0; db < 2; ++db)
; #pragma unroll
;         for (int cb = 0; cb < 2; ++cb)
; #pragma unroll
;             for (int i = 0; i < 16; ++i) o[db][cb][i] = 0.f;
;     float rs[2] = {0.f, 0.f};
;     f32x16 negm;
; #pragma unroll
;     for (int i = 0; i < 16; ++i) negm[i] = -mshift;
; __device__ __forceinline__ void mk_p3(const Ptrs& P, LAS unsigned char* lds, int tid, int wave, int lane, int bx, int G, bool dry) {
;     ...
;         { bool pre = false; for (int u = bx; u < NB * 32 * 4; u += G) pre = attn_unit(P, lds, u, tid, wave, lane, pre, u + G < NB * 32 * 4 ? u + G : -1); }
.LBB9_305:
	s_cmp_lt_i32 s92, 4
	s_cselect_b64 s[2:3], -1, 0
	s_and_b64 s[22:23], s[2:3], s[0:1]
	s_andn2_b64 vcc, exec, s[22:23]
	s_cbranch_vccnz .LBB9_444
	v_writelane_b32 v251, s22, 33
	s_cmpk_gt_i32 s97, 0x1ff
	v_and_b32_e32 v171, 31, v208
	v_writelane_b32 v251, s23, 34
	v_writelane_b32 v251, s80, 35
	v_lshrrev_b32_e32 v184, 5, v170
	s_nop 0
	v_writelane_b32 v251, s81, 36
	v_writelane_b32 v251, s96, 37
	v_writelane_b32 v251, s83, 38
	v_writelane_b32 v251, s97, 39
	s_cbranch_scc1 .LBB9_413
	v_mbcnt_lo_u32_b32 v0, -1, 0
	v_mbcnt_hi_u32_b32 v0, -1, v0
	v_and_b32_e32 v1, 64, v0
	v_add_u32_e32 v1, 64, v1
	v_xor_b32_e32 v2, 1, v0
	v_cmp_lt_i32_e32 vcc, v2, v1
	s_bfe_u32 s0, s40, 0x20006
	v_writelane_b32 v251, s0, 40
	v_cndmask_b32_e32 v2, v0, v2, vcc
	v_lshlrev_b32_e32 v185, 2, v2
	v_xor_b32_e32 v2, 2, v0
	v_cmp_lt_i32_e32 vcc, v2, v1
	s_lshl_b32 s0, s50, 4
	s_and_b32 s33, s0, 0x3fffffc0
	v_cndmask_b32_e32 v2, v0, v2, vcc
	v_lshlrev_b32_e32 v186, 2, v2
	v_xor_b32_e32 v2, 4, v0
	v_cmp_lt_i32_e32 vcc, v2, v1
	s_cmpk_lt_u32 s40, 0x8c0
	s_cselect_b64 s[54:55], -1, 0
	v_cndmask_b32_e32 v2, v0, v2, vcc
	v_lshlrev_b32_e32 v187, 2, v2
	v_xor_b32_e32 v2, 8, v0
	v_cmp_lt_i32_e32 vcc, v2, v1
	s_or_b32 s2, s0, 63
	s_or_b32 s3, s33, 32
	v_cndmask_b32_e32 v2, v0, v2, vcc
	v_lshlrev_b32_e32 v188, 2, v2
	v_xor_b32_e32 v2, 16, v0
	v_cmp_lt_i32_e32 vcc, v2, v1
	v_or_b32_e32 v5, 32, v170
	v_lshlrev_b32_e32 v191, 4, v184
	v_cndmask_b32_e32 v2, v0, v2, vcc
	v_lshlrev_b32_e32 v189, 2, v2
	v_xor_b32_e32 v2, 32, v0
	v_cmp_lt_i32_e32 vcc, v2, v1
	v_mov_b32_e32 v1, 0
	v_mul_u32_u24_e32 v6, 0x110, v5
	v_cndmask_b32_e32 v0, v0, v2, vcc
	v_lshlrev_b32_e32 v190, 2, v0
	v_lshlrev_b32_e32 v0, 2, v184
	v_sub_u32_e32 v0, v171, v0
	v_cmp_lt_i32_e64 s[36:37], 10, v0
	v_cmp_gt_i32_e64 s[0:1], 1, v0
	v_cmp_gt_i32_e64 s[4:5], 2, v0
	v_writelane_b32 v251, s36, 41
	v_cmp_gt_i32_e64 s[6:7], 3, v0
	v_cmp_gt_i32_e64 s[8:9], 4, v0
	v_writelane_b32 v251, s37, 42
	v_cmp_lt_i32_e64 s[36:37], 15, v0
	v_cmp_gt_i32_e64 s[10:11], 9, v0
	v_cmp_gt_i32_e64 s[12:13], 10, v0
	v_writelane_b32 v251, s36, 43
	v_cmp_gt_i32_e64 s[14:15], 11, v0
	v_cmp_gt_i32_e64 s[16:17], 12, v0
	v_writelane_b32 v251, s37, 44
	v_cmp_lt_i32_e64 s[36:37], 16, v0
	v_cmp_gt_i32_e64 s[18:19], 17, v0
	v_cmp_gt_i32_e64 s[20:21], 18, v0
	v_writelane_b32 v251, s36, 45
	v_cmp_gt_i32_e64 s[22:23], 19, v0
	v_cmp_gt_i32_e64 s[24:25], 20, v0
	v_writelane_b32 v251, s37, 46
	v_cmp_lt_i32_e64 s[36:37], 17, v0
	v_cmp_gt_i32_e64 s[26:27], 25, v0
	v_cmp_gt_i32_e64 s[28:29], 26, v0
	v_writelane_b32 v251, s36, 47
	v_cmp_gt_i32_e64 s[30:31], 27, v0
	v_cmp_gt_i32_e64 s[34:35], 28, v0
	v_writelane_b32 v251, s37, 48
	v_cmp_lt_i32_e64 s[36:37], 18, v0
	v_cmp_lt_i32_e64 s[56:57], -1, v0
	v_cmp_lt_i32_e64 s[86:87], 0, v0
	v_writelane_b32 v251, s36, 49
	v_cmp_lt_i32_e64 s[60:61], 1, v0
	v_cmp_lt_i32_e64 s[62:63], 2, v0
	v_writelane_b32 v251, s37, 50
	v_cmp_lt_i32_e64 s[36:37], 23, v0
	v_cmp_lt_i32_e64 s[64:65], 7, v0
	v_cmp_lt_i32_e64 s[66:67], 8, v0
	v_writelane_b32 v251, s36, 51
	v_cmp_lt_i32_e64 s[72:73], 9, v0
	v_lshlrev_b32_e32 v4, 3, v184
	v_writelane_b32 v251, s37, 52
	v_cmp_lt_i32_e64 s[36:37], 24, v0
	v_mul_u32_u24_e32 v3, 0x110, v171
	v_lshlrev_b32_e32 v2, 10, v171
	v_writelane_b32 v251, s36, 53
	s_movk_i32 s52, 0x110
	v_add3_u32 v3, v3, v191, 0
	v_writelane_b32 v251, s37, 54
	v_cmp_lt_i32_e64 s[36:37], 25, v0
	v_lshlrev_b32_e32 v176, 1, v4
	s_mov_b32 s77, 0
	v_writelane_b32 v251, s36, 55
	v_add_u32_e32 v195, 0x4800, v3
	v_add_u32_e32 v198, 0xd400, v3
	v_writelane_b32 v251, s37, 56
	v_cmp_lt_i32_e64 s[36:37], 26, v0
	v_lshlrev_b32_e32 v0, 2, v170
	v_mad_u32_u24 v200, v5, s52, 0
	v_writelane_b32 v251, s36, 57
	v_mad_u32_u24 v201, v171, s52, 0
	s_mov_b64 s[68:69], 0
	v_writelane_b32 v251, s37, 58
	s_add_u32 s36, s90, 0x6200000
	v_writelane_b32 v251, s36, 59
	s_addc_u32 s36, s91, 0
	v_writelane_b32 v251, s36, 60
	s_add_u32 s36, s90, 0x7200000
	v_writelane_b32 v251, s36, 61
	s_addc_u32 s36, s91, 0
	v_writelane_b32 v251, s36, 62
	v_mov_b32_e32 v178, v176
	v_readlane_b32 s36, v251, 16
	s_add_u32 s36, s90, 0x4200000
	v_readlane_b32 s37, v251, 17
	v_readlane_b32 s38, v251, 18
	v_readlane_b32 s39, v251, 19
	v_readlane_b32 s40, v251, 20
	v_readlane_b32 s41, v251, 21
	v_readlane_b32 s42, v251, 22
	v_readlane_b32 s43, v251, 23
	v_readlane_b32 s44, v251, 24
	v_readlane_b32 s45, v251, 25
	v_readlane_b32 s46, v251, 26
	v_readlane_b32 s47, v251, 27
	v_readlane_b32 s48, v251, 28
	v_readlane_b32 s49, v251, 29
	v_readlane_b32 s50, v251, 30
	v_readlane_b32 s51, v251, 31
	v_writelane_b32 v251, s36, 63
	s_addc_u32 s36, s91, 0
	v_writelane_b32 v250, s36, 0
	s_add_u32 s36, s90, 0x6a00000
	v_writelane_b32 v250, s36, 1
	s_addc_u32 s36, s91, 0
	v_writelane_b32 v250, s36, 2
	s_add_u32 s36, s90, 0x7280000
	v_writelane_b32 v250, s36, 3
	s_addc_u32 s36, s91, 0
	v_writelane_b32 v250, s36, 4
	s_add_u32 s36, s90, 0x2000000
	v_writelane_b32 v250, s36, 5
	s_addc_u32 s36, s91, 0
	v_lshl_add_u64 v[172:173], s[40:41], 0, v[0:1]
	v_writelane_b32 v250, s36, 6
	s_add_i32 s40, 0, 0x11800
	s_add_i32 s76, 0, 0x16000
	v_writelane_b32 v250, s40, 7
	v_writelane_b32 v250, s76, 8
	v_writelane_b32 v250, s88, 9
	v_lshl_add_u64 v[174:175], s[42:43], 0, v[0:1]
	v_readlane_b32 s36, v251, 32
	v_writelane_b32 v250, s89, 10
	v_writelane_b32 v250, s90, 11
	v_writelane_b32 v250, s91, 12
	v_add3_u32 v0, v6, v191, 0
	v_mul_u32_u24_e32 v6, 0x90, v171
	v_writelane_b32 v250, s92, 13
	v_lshl_or_b32 v192, s36, 6, v170
	s_movk_i32 s37, 0x90
	v_add3_u32 v196, v6, v191, 0
	v_writelane_b32 v250, s93, 14
	v_add_u32_e32 v193, 0xfffffb80, v192
	v_add_u32_e32 v194, 0x4800, v0
	v_add_u32_e32 v197, 0xd400, v0
	v_add_u32_e32 v199, 0x8c00, v196
	v_mad_u32_u24 v202, v171, s37, 0
	v_mov_b32_e32 v179, v1
	v_lshlrev_b32_e32 v180, 1, v2
	v_mov_b32_e32 v181, v1
	s_mov_b32 s36, 0xf0f0f0f1
	s_movk_i32 s37, 0xffef
	s_movk_i32 s38, 0x490
	s_mov_b32 s39, 0x38e38e39
	v_readlane_b32 s42, v251, 39
	v_writelane_b32 v250, s94, 22
	v_writelane_b32 v250, s94, 23
	v_mov_b32_e32 v254, 0x24008
	ds_read_b32 v254, v254
	s_waitcnt lgkmcnt(0)
	v_readfirstlane_b32 s98, v254
	s_nop 3
	s_cmp_eq_u32 s98, 1
	s_cbranch_scc0 .Lrm_a
	s_cmpk_lg_i32 s94, 0x100
	s_cbranch_scc1 .Lrm_a
	s_and_b32 s98, s42, 7
	s_lshl_b32 s98, s98, 3
	s_bfe_u32 s99, s42, 0x30003
	s_or_b32 s98, s98, s99
	s_and_b32 vcc_lo, s98, 7
	s_lshl_b32 vcc_lo, vcc_lo, 3
	s_lshr_b32 vcc_hi, s98, 3
	s_or_b32 vcc_lo, vcc_lo, vcc_hi
	s_mov_b32 vcc_lo, s98
